# scan rotary write blocks regenerated with packed f32 ops paired over adjacent features (no pair-building v_mov, bit-identical), on top of previous best
# speedup vs baseline: 1.0017x; 1.0017x over previous
.LBB0_201:
	s_add_i32 s38, s34, -4
	s_add_i32 s6, s35, 4
	s_and_b64 s[0:1], s[36:37], exec
	s_cselect_b32 s0, s38, s6
	s_or_b32 s0, s0, s31
	s_ashr_i32 s1, s0, 31
	s_lshl_b64 s[0:1], s[0:1], 15
	v_lshl_add_u64 v[136:137], v[134:135], 0, s[0:1]
	v_cvt_pk_bf16_f32 v144, v56, v57
	v_cvt_pk_bf16_f32 v145, v58, v59
	global_store_dwordx2 v[136:137], v[144:145], off
	v_cvt_pk_bf16_f32 v144, v116, v117
	v_cvt_pk_bf16_f32 v145, v118, v119
	global_store_dwordx2 v[136:137], v[144:145], off offset:32
	v_cvt_pk_bf16_f32 v144, v120, v121
	v_cvt_pk_bf16_f32 v145, v122, v123
	global_store_dwordx2 v[136:137], v[144:145], off offset:64
	v_cvt_pk_bf16_f32 v144, v124, v125
	v_cvt_pk_bf16_f32 v145, v126, v127
	global_store_dwordx2 v[136:137], v[144:145], off offset:96
	ds_read_b128 v[208:211], v192
	ds_read_b128 v[212:215], v193 offset:4352
	ds_read_b128 v[216:219], v192 offset:8704
	ds_read_b128 v[220:223], v193 offset:13056
	ds_read_b128 v[228:231], v195
	ds_read_b128 v[232:235], v196 offset:4352
	ds_read_b128 v[236:239], v195 offset:8704
	ds_read_b128 v[240:243], v196 offset:13056
	s_waitcnt vmcnt(8)
	v_add_u32_e32 v147, 0x4400, v189
	v_lshlrev_b32_e32 v136, 16, v0
	v_and_b32_e32 v137, 0xffff0000, v0
	v_lshlrev_b32_e32 v144, 16, v4
	v_and_b32_e32 v145, 0xffff0000, v4
	v_lshlrev_b32_e32 v148, 16, v8
	v_and_b32_e32 v149, 0xffff0000, v8
	v_lshlrev_b32_e32 v150, 16, v12
	v_and_b32_e32 v151, 0xffff0000, v12
	v_pk_mul_f32 v[152:153], v[36:37], v[144:145]
	v_pk_mul_f32 v[144:145], v[28:29], v[144:145]
	v_pk_fma_f32 v[152:153], v[28:29], v[136:137], v[152:153] neg_lo:[0,0,1] neg_hi:[0,0,1]
	v_pk_fma_f32 v[136:137], v[36:37], v[136:137], v[144:145]
	v_pk_mul_f32 v[144:145], v[52:53], v[150:151]
	v_pk_mul_f32 v[150:151], v[44:45], v[150:151]
	v_pk_fma_f32 v[144:145], v[44:45], v[148:149], v[144:145] neg_lo:[0,0,1] neg_hi:[0,0,1]
	v_pk_fma_f32 v[148:149], v[52:53], v[148:149], v[150:151]
	v_cvt_pk_bf16_f32 v152, v152, v144
	v_cvt_pk_bf16_f32 v153, v153, v145
	v_cvt_pk_bf16_f32 v136, v136, v148
	v_cvt_pk_bf16_f32 v137, v137, v149
	v_lshlrev_b32_e32 v144, 16, v16
	v_lshlrev_b32_e32 v145, 16, v20
	v_pk_mul_f32 v[144:145], v[170:171], v[144:145]
	v_and_b32_e32 v148, 0xffff0000, v16
	v_and_b32_e32 v149, 0xffff0000, v20
	v_pk_mul_f32 v[148:149], v[170:171], v[148:149]
	v_cvt_pk_bf16_f32 v150, v144, v145
	v_cvt_pk_bf16_f32 v151, v148, v149
	ds_write2_b32 v189, v152, v153 offset1:68
	ds_write2_b32 v147, v136, v137 offset1:68
	ds_write2_b32 v190, v150, v151 offset1:68
	v_lshlrev_b32_e32 v136, 16, v1
	v_and_b32_e32 v137, 0xffff0000, v1
	v_lshlrev_b32_e32 v144, 16, v5
	v_and_b32_e32 v145, 0xffff0000, v5
	v_lshlrev_b32_e32 v148, 16, v9
	v_and_b32_e32 v149, 0xffff0000, v9
	v_lshlrev_b32_e32 v150, 16, v13
	v_and_b32_e32 v151, 0xffff0000, v13
	v_pk_mul_f32 v[152:153], v[38:39], v[144:145]
	v_pk_mul_f32 v[144:145], v[30:31], v[144:145]
	v_pk_fma_f32 v[152:153], v[30:31], v[136:137], v[152:153] neg_lo:[0,0,1] neg_hi:[0,0,1]
	v_pk_fma_f32 v[136:137], v[38:39], v[136:137], v[144:145]
	v_pk_mul_f32 v[144:145], v[54:55], v[150:151]
	v_pk_mul_f32 v[150:151], v[46:47], v[150:151]
	v_pk_fma_f32 v[144:145], v[46:47], v[148:149], v[144:145] neg_lo:[0,0,1] neg_hi:[0,0,1]
	v_pk_fma_f32 v[148:149], v[54:55], v[148:149], v[150:151]
	v_cvt_pk_bf16_f32 v152, v152, v144
	v_cvt_pk_bf16_f32 v153, v153, v145
	v_cvt_pk_bf16_f32 v136, v136, v148
	v_cvt_pk_bf16_f32 v137, v137, v149
	v_lshlrev_b32_e32 v144, 16, v17
	v_lshlrev_b32_e32 v145, 16, v21
	v_pk_mul_f32 v[144:145], v[170:171], v[144:145]
	v_and_b32_e32 v148, 0xffff0000, v17
	v_and_b32_e32 v149, 0xffff0000, v21
	v_pk_mul_f32 v[148:149], v[170:171], v[148:149]
	v_cvt_pk_bf16_f32 v150, v144, v145
	v_cvt_pk_bf16_f32 v151, v148, v149
	ds_write2_b32 v189, v152, v153 offset0:136 offset1:204
	ds_write2_b32 v147, v136, v137 offset0:136 offset1:204
	ds_write2_b32 v190, v150, v151 offset0:136 offset1:204
	v_add_u32_e32 v167, 0xd000, v187
	v_add_u32_e32 v147, 0x4800, v189
	v_add_u32_e32 v141, 0x400, v190
	v_lshlrev_b32_e32 v136, 16, v2
	v_and_b32_e32 v137, 0xffff0000, v2
	v_lshlrev_b32_e32 v144, 16, v6
	v_and_b32_e32 v145, 0xffff0000, v6
	v_lshlrev_b32_e32 v148, 16, v10
	v_and_b32_e32 v149, 0xffff0000, v10
	v_lshlrev_b32_e32 v150, 16, v14
	v_and_b32_e32 v151, 0xffff0000, v14
	v_pk_mul_f32 v[152:153], v[32:33], v[144:145]
	v_pk_mul_f32 v[144:145], v[24:25], v[144:145]
	v_pk_fma_f32 v[152:153], v[24:25], v[136:137], v[152:153] neg_lo:[0,0,1] neg_hi:[0,0,1]
	v_pk_fma_f32 v[136:137], v[32:33], v[136:137], v[144:145]
	v_pk_mul_f32 v[144:145], v[48:49], v[150:151]
	v_pk_mul_f32 v[150:151], v[40:41], v[150:151]
	v_pk_fma_f32 v[144:145], v[40:41], v[148:149], v[144:145] neg_lo:[0,0,1] neg_hi:[0,0,1]
	v_pk_fma_f32 v[148:149], v[48:49], v[148:149], v[150:151]
	v_cvt_pk_bf16_f32 v152, v152, v144
	v_cvt_pk_bf16_f32 v153, v153, v145
	v_cvt_pk_bf16_f32 v136, v136, v148
	v_cvt_pk_bf16_f32 v137, v137, v149
	v_lshlrev_b32_e32 v144, 16, v18
	v_lshlrev_b32_e32 v145, 16, v22
	v_pk_mul_f32 v[144:145], v[170:171], v[144:145]
	v_and_b32_e32 v148, 0xffff0000, v18
	v_and_b32_e32 v149, 0xffff0000, v22
	v_pk_mul_f32 v[148:149], v[170:171], v[148:149]
	v_cvt_pk_bf16_f32 v150, v144, v145
	v_cvt_pk_bf16_f32 v151, v148, v149
	ds_write2_b32 v167, v152, v153 offset0:16 offset1:84
	ds_write2_b32 v147, v136, v137 offset0:16 offset1:84
	ds_write2_b32 v141, v150, v151 offset0:16 offset1:84
	v_lshlrev_b32_e32 v136, 16, v3
	v_and_b32_e32 v137, 0xffff0000, v3
	v_lshlrev_b32_e32 v144, 16, v7
	v_and_b32_e32 v145, 0xffff0000, v7
	v_lshlrev_b32_e32 v148, 16, v11
	v_and_b32_e32 v149, 0xffff0000, v11
	v_lshlrev_b32_e32 v150, 16, v15
	v_and_b32_e32 v151, 0xffff0000, v15
	v_pk_mul_f32 v[152:153], v[34:35], v[144:145]
	v_pk_mul_f32 v[144:145], v[26:27], v[144:145]
	v_pk_fma_f32 v[152:153], v[26:27], v[136:137], v[152:153] neg_lo:[0,0,1] neg_hi:[0,0,1]
	v_pk_fma_f32 v[136:137], v[34:35], v[136:137], v[144:145]
	v_pk_mul_f32 v[144:145], v[50:51], v[150:151]
	v_pk_mul_f32 v[150:151], v[42:43], v[150:151]
	v_pk_fma_f32 v[144:145], v[42:43], v[148:149], v[144:145] neg_lo:[0,0,1] neg_hi:[0,0,1]
	v_pk_fma_f32 v[148:149], v[50:51], v[148:149], v[150:151]
	v_cvt_pk_bf16_f32 v152, v152, v144
	v_cvt_pk_bf16_f32 v153, v153, v145
	v_cvt_pk_bf16_f32 v136, v136, v148
	v_cvt_pk_bf16_f32 v137, v137, v149
	v_lshlrev_b32_e32 v144, 16, v19
	v_lshlrev_b32_e32 v145, 16, v23
	v_pk_mul_f32 v[144:145], v[170:171], v[144:145]
	v_and_b32_e32 v148, 0xffff0000, v19
	v_and_b32_e32 v149, 0xffff0000, v23
	v_pk_mul_f32 v[148:149], v[170:171], v[148:149]
	v_cvt_pk_bf16_f32 v150, v144, v145
	v_cvt_pk_bf16_f32 v151, v148, v149
	ds_write2_b32 v167, v152, v153 offset0:152 offset1:220
	ds_write2_b32 v147, v136, v137 offset0:152 offset1:220
	ds_write2_b32 v141, v150, v151 offset0:152 offset1:220
	s_cmp_gt_u32 s38, 27
	ds_read_b128 v[148:151], v191 offset:34816
	ds_read_b128 v[224:227], v194 offset:34816
	s_cbranch_scc1 .LBB0_203
	s_add_i32 s6, s34, -1
	s_add_i32 s17, s35, 1
	s_and_b64 s[0:1], s[36:37], exec
	s_cselect_b32 s0, s6, s17
	v_lshl_add_u32 v24, s0, 7, v183
	v_add_u32_e32 v2, s29, v24
	v_mov_b64_e32 v[0:1], s[14:15]
	v_mad_i64_i32 v[16:17], s[0:1], v2, s59, v[0:1]
	v_lshl_add_u64 v[8:9], v[16:17], 0, v[154:155]
	s_lshl_b32 s6, s30, 1
	v_add_co_u32_e32 v12, vcc, 0x2000, v8
	v_lshl_add_u64 v[16:17], v[16:17], 0, s[6:7]
	v_lshlrev_b32_e32 v24, 6, v24
	v_addc_co_u32_e32 v13, vcc, 0, v9, vcc
	v_lshl_add_u64 v[16:17], v[16:17], 0, v[154:155]
	v_ashrrev_i32_e32 v25, 31, v24
	v_add_co_u32_e32 v20, vcc, 0x2000, v16
	v_lshlrev_b64 v[24:25], 2, v[24:25]
	s_nop 0
	v_addc_co_u32_e32 v21, vcc, 0, v17, vcc
	v_lshl_add_u64 v[44:45], v[160:161], 0, v[24:25]
	v_lshl_add_u64 v[52:53], v[162:163], 0, v[24:25]
	global_load_dwordx4 v[0:3], v[8:9], off offset:1536
	global_load_dwordx4 v[4:7], v[8:9], off offset:1664
	s_nop 0
	global_load_dwordx4 v[8:11], v[12:13], off
	s_nop 0
	global_load_dwordx4 v[12:15], v[12:13], off offset:128
	s_nop 0
	global_load_dwordx4 v[16:19], v[16:17], off offset:3072
	s_nop 0
	global_load_dwordx4 v[20:23], v[20:21], off offset:1536
	s_nop 0
	global_load_dwordx4 v[24:27], v[44:45], off offset:16
	global_load_dwordx4 v[28:31], v[44:45], off
	global_load_dwordx4 v[32:35], v[52:53], off offset:16
	global_load_dwordx4 v[36:39], v[52:53], off
	global_load_dwordx4 v[40:43], v[44:45], off offset:272
	s_nop 0
	global_load_dwordx4 v[44:47], v[44:45], off offset:256
	s_nop 0
	global_load_dwordx4 v[48:51], v[52:53], off offset:272
	s_nop 0
	global_load_dwordx4 v[52:55], v[52:53], off offset:256
.LBB0_203:
	v_mov_b32_e32 v129, v128
	v_pk_mul_f32 v[58:59], v[128:129], v[58:59]
	v_pk_mul_f32 v[56:57], v[130:131], v[56:57]
	v_pk_mul_f32 v[118:119], v[128:129], v[118:119]
	v_pk_mul_f32 v[116:117], v[130:131], v[116:117]
	v_pk_mul_f32 v[122:123], v[128:129], v[122:123]
	v_pk_mul_f32 v[120:121], v[130:131], v[120:121]
	v_pk_mul_f32 v[126:127], v[128:129], v[126:127]
	v_pk_mul_f32 v[124:125], v[130:131], v[124:125]
	s_setprio 1
	s_waitcnt lgkmcnt(0)
	v_mfma_f32_16x16x32_bf16 v[56:59], v[208:211], v[148:151], v[56:59]
	s_waitcnt lgkmcnt(7)
	v_mfma_f32_16x16x32_bf16 v[116:119], v[212:215], v[148:151], v[116:119]
	s_waitcnt lgkmcnt(6)
	v_mfma_f32_16x16x32_bf16 v[120:123], v[216:219], v[148:151], v[120:123]
	s_waitcnt lgkmcnt(5)
	v_mfma_f32_16x16x32_bf16 v[124:127], v[220:223], v[148:151], v[124:127]
	s_waitcnt lgkmcnt(3)
	v_mfma_f32_16x16x32_bf16 v[56:59], v[228:231], v[224:227], v[56:59]
	s_waitcnt lgkmcnt(2)
	v_mfma_f32_16x16x32_bf16 v[116:119], v[232:235], v[224:227], v[116:119]
	s_waitcnt lgkmcnt(1)
	v_mfma_f32_16x16x32_bf16 v[120:123], v[236:239], v[224:227], v[120:123]
	s_waitcnt lgkmcnt(0)
	v_mfma_f32_16x16x32_bf16 v[124:127], v[240:243], v[224:227], v[124:127]
	s_setprio 0
	ds_read_b128 v[148:151], v197 offset:34816
	ds_read_b128 v[208:211], v198
	ds_read_b128 v[212:215], v199 offset:4352
	ds_read_b128 v[216:219], v198 offset:8704
	ds_read_b128 v[220:223], v199 offset:13056
	ds_read_b128 v[224:227], v200 offset:34816
	ds_read_b128 v[228:231], v201
	ds_read_b128 v[232:235], v201 offset:8704
	ds_read_b128 v[236:239], v202 offset:4352
	ds_read_b128 v[240:243], v202 offset:13056
	s_setprio 1
	s_waitcnt lgkmcnt(8)
	v_mfma_f32_16x16x32_bf16 v[56:59], v[208:211], v[148:151], v[56:59]
	s_waitcnt lgkmcnt(7)
	v_mfma_f32_16x16x32_bf16 v[116:119], v[212:215], v[148:151], v[116:119]
	s_waitcnt lgkmcnt(6)
	v_mfma_f32_16x16x32_bf16 v[208:211], v[216:219], v[148:151], v[120:123]
	s_waitcnt lgkmcnt(5)
	v_mfma_f32_16x16x32_bf16 v[148:151], v[220:223], v[148:151], v[124:127]
	s_waitcnt lgkmcnt(3)
	v_mfma_f32_16x16x32_bf16 v[124:127], v[228:231], v[224:227], v[56:59]
	s_waitcnt lgkmcnt(1)
	v_mfma_f32_16x16x32_bf16 v[120:123], v[236:239], v[224:227], v[116:119]
	v_mfma_f32_16x16x32_bf16 v[116:119], v[232:235], v[224:227], v[208:211]
	s_waitcnt lgkmcnt(0)
	v_mfma_f32_16x16x32_bf16 v[56:59], v[240:243], v[224:227], v[148:151]
	s_setprio 0
	s_add_i32 s6, s34, -3
	s_add_i32 s17, s35, 3
	s_and_b64 s[0:1], s[36:37], exec
	s_cselect_b32 s0, s6, s17
	s_or_b32 s0, s0, s31
	s_ashr_i32 s1, s0, 31
	s_lshl_b64 s[0:1], s[0:1], 15
	v_lshl_add_u64 v[136:137], v[134:135], 0, s[0:1]
	v_cvt_pk_bf16_f32 v144, v124, v125
	v_cvt_pk_bf16_f32 v145, v126, v127
	s_waitcnt lgkmcnt(0)
	s_barrier
; #define SCAN_STORE(st) do { \
;             bf16_t* sp = states + ((size_t)((bh * 2 + dir) * 32 + SCAN_NCH(st))) * 16384 + (64 * half + 16 * et + fr) * 128 + 16 * dbase + 4 * fq; \
;             _Pragma("unroll") for (int dt = 0; dt < 4; ++dt) { u32x2 w; w.x = cvt_pk_bf16(acc[dt][0], acc[dt][1]); w.y = cvt_pk_bf16(acc[dt][2], acc[dt][3]); *(u32x2*)(sp + 16 * dt) = w; } } while (0)
; #define SCAN_BAR() do { asm volatile("s_waitcnt lgkmcnt(0)" ::: "memory"); __builtin_amdgcn_s_barrier(); asm volatile("" ::: "memory"); } while (0)
; __device__ __forceinline__ void ret_scan(const bf16_t* proj, const float* cosT, const float* sinT, const float* decay, bf16_t* states, unsigned char* lds, int tid, int bx) {
;     ...
;         SCAN_LOAD(A, SCAN_NCH(0)); SCAN_LOAD(B, SCAN_NCH(1));
;         SCAN_WRITE(A, 0);
;         SCAN_LOAD(A, SCAN_NCH(2));
;         SCAN_BAR();
;         for (int step = 0; step < 30; step += 2) {
;             SCAN_STORE(step);
; #pragma unroll
;             for (int dt = 0; dt < 4; ++dt) acc[dt] *= cdec;
;             SCAN_WRITE(B, 1); if (step + 3 <= 30) SCAN_LOAD(B, SCAN_NCH(step + 3));
;             SCAN_MMA(0);
;             SCAN_BAR();
;             SCAN_STORE(step + 1);
; #pragma unroll
;             for (int dt = 0; dt < 4; ++dt) acc[dt] *= cdec;
;             SCAN_WRITE(A, 0); if (step + 4 <= 30) SCAN_LOAD(A, SCAN_NCH(step + 4));
;             SCAN_MMA(1);
	global_store_dwordx2 v[136:137], v[144:145], off
	v_cvt_pk_bf16_f32 v144, v120, v121
	v_cvt_pk_bf16_f32 v145, v122, v123
	global_store_dwordx2 v[136:137], v[144:145], off offset:32
	v_cvt_pk_bf16_f32 v144, v116, v117
	v_cvt_pk_bf16_f32 v145, v118, v119
	global_store_dwordx2 v[136:137], v[144:145], off offset:64
	v_cvt_pk_bf16_f32 v144, v56, v57
	v_cvt_pk_bf16_f32 v145, v58, v59
	global_store_dwordx2 v[136:137], v[144:145], off offset:96
	ds_read_b128 v[208:211], v192 offset:52224
	ds_read_b128 v[212:215], v193 offset:56576
	ds_read_b128 v[216:219], v192 offset:60928
	ds_read_b128 v[220:223], v193 offset:65280
	ds_read_b128 v[228:231], v195 offset:52224
	ds_read_b128 v[232:235], v196 offset:56576
	ds_read_b128 v[236:239], v195 offset:60928
	ds_read_b128 v[240:243], v196 offset:65280
	s_waitcnt vmcnt(8)
	v_lshlrev_b32_e32 v136, 16, v60
	v_and_b32_e32 v137, 0xffff0000, v60
	v_lshlrev_b32_e32 v144, 16, v64
	v_and_b32_e32 v145, 0xffff0000, v64
	v_lshlrev_b32_e32 v148, 16, v68
	v_and_b32_e32 v149, 0xffff0000, v68
	v_lshlrev_b32_e32 v150, 16, v72
	v_and_b32_e32 v151, 0xffff0000, v72
	v_pk_mul_f32 v[152:153], v[96:97], v[144:145]
	v_pk_mul_f32 v[144:145], v[88:89], v[144:145]
	v_pk_fma_f32 v[152:153], v[88:89], v[136:137], v[152:153] neg_lo:[0,0,1] neg_hi:[0,0,1]
	v_pk_fma_f32 v[136:137], v[96:97], v[136:137], v[144:145]
	v_pk_mul_f32 v[144:145], v[112:113], v[150:151]
	v_pk_mul_f32 v[150:151], v[104:105], v[150:151]
	v_pk_fma_f32 v[144:145], v[104:105], v[148:149], v[144:145] neg_lo:[0,0,1] neg_hi:[0,0,1]
	v_pk_fma_f32 v[148:149], v[112:113], v[148:149], v[150:151]
	v_cvt_pk_bf16_f32 v152, v152, v144
	v_cvt_pk_bf16_f32 v153, v153, v145
	v_cvt_pk_bf16_f32 v136, v136, v148
	v_cvt_pk_bf16_f32 v137, v137, v149
	v_lshlrev_b32_e32 v144, 16, v76
	v_lshlrev_b32_e32 v145, 16, v80
	v_pk_mul_f32 v[144:145], v[170:171], v[144:145]
	v_and_b32_e32 v148, 0xffff0000, v76
	v_and_b32_e32 v149, 0xffff0000, v80
	v_pk_mul_f32 v[148:149], v[170:171], v[148:149]
	v_cvt_pk_bf16_f32 v150, v144, v145
	v_cvt_pk_bf16_f32 v151, v148, v149
	ds_write2_b32 v187, v152, v153 offset1:68
	ds_write2_b32 v146, v136, v137 offset1:68
	ds_write2_b32 v138, v150, v151 offset1:68
	v_lshlrev_b32_e32 v136, 16, v61
	v_and_b32_e32 v137, 0xffff0000, v61
	v_lshlrev_b32_e32 v144, 16, v65
	v_and_b32_e32 v145, 0xffff0000, v65
	v_lshlrev_b32_e32 v148, 16, v69
	v_and_b32_e32 v149, 0xffff0000, v69
	v_lshlrev_b32_e32 v150, 16, v73
	v_and_b32_e32 v151, 0xffff0000, v73
	v_pk_mul_f32 v[152:153], v[98:99], v[144:145]
	v_pk_mul_f32 v[144:145], v[90:91], v[144:145]
	v_pk_fma_f32 v[152:153], v[90:91], v[136:137], v[152:153] neg_lo:[0,0,1] neg_hi:[0,0,1]
	v_pk_fma_f32 v[136:137], v[98:99], v[136:137], v[144:145]
	v_pk_mul_f32 v[144:145], v[114:115], v[150:151]
	v_pk_mul_f32 v[150:151], v[106:107], v[150:151]
	v_pk_fma_f32 v[144:145], v[106:107], v[148:149], v[144:145] neg_lo:[0,0,1] neg_hi:[0,0,1]
	v_pk_fma_f32 v[148:149], v[114:115], v[148:149], v[150:151]
	v_cvt_pk_bf16_f32 v152, v152, v144
	v_cvt_pk_bf16_f32 v153, v153, v145
	v_cvt_pk_bf16_f32 v136, v136, v148
	v_cvt_pk_bf16_f32 v137, v137, v149
	v_lshlrev_b32_e32 v144, 16, v77
	v_lshlrev_b32_e32 v145, 16, v81
	v_pk_mul_f32 v[144:145], v[170:171], v[144:145]
	v_and_b32_e32 v148, 0xffff0000, v77
	v_and_b32_e32 v149, 0xffff0000, v81
	v_pk_mul_f32 v[148:149], v[170:171], v[148:149]
	v_cvt_pk_bf16_f32 v150, v144, v145
	v_cvt_pk_bf16_f32 v151, v148, v149
	ds_write2_b32 v187, v152, v153 offset0:136 offset1:204
	ds_write2_b32 v146, v136, v137 offset0:136 offset1:204
	ds_write2_b32 v138, v150, v151 offset0:136 offset1:204
	v_lshlrev_b32_e32 v136, 16, v62
	v_and_b32_e32 v137, 0xffff0000, v62
	v_lshlrev_b32_e32 v144, 16, v66
	v_and_b32_e32 v145, 0xffff0000, v66
	v_lshlrev_b32_e32 v148, 16, v70
	v_and_b32_e32 v149, 0xffff0000, v70
	v_lshlrev_b32_e32 v150, 16, v74
	v_and_b32_e32 v151, 0xffff0000, v74
	v_pk_mul_f32 v[152:153], v[92:93], v[144:145]
	v_pk_mul_f32 v[144:145], v[84:85], v[144:145]
	v_pk_fma_f32 v[152:153], v[84:85], v[136:137], v[152:153] neg_lo:[0,0,1] neg_hi:[0,0,1]
	v_pk_fma_f32 v[136:137], v[92:93], v[136:137], v[144:145]
	v_pk_mul_f32 v[144:145], v[108:109], v[150:151]
	v_pk_mul_f32 v[150:151], v[100:101], v[150:151]
	v_pk_fma_f32 v[144:145], v[100:101], v[148:149], v[144:145] neg_lo:[0,0,1] neg_hi:[0,0,1]
	v_pk_fma_f32 v[148:149], v[108:109], v[148:149], v[150:151]
	v_cvt_pk_bf16_f32 v152, v152, v144
	v_cvt_pk_bf16_f32 v153, v153, v145
	v_cvt_pk_bf16_f32 v136, v136, v148
	v_cvt_pk_bf16_f32 v137, v137, v149
	v_lshlrev_b32_e32 v144, 16, v78
	v_lshlrev_b32_e32 v145, 16, v82
	v_pk_mul_f32 v[144:145], v[170:171], v[144:145]
	v_and_b32_e32 v148, 0xffff0000, v78
	v_and_b32_e32 v149, 0xffff0000, v82
	v_pk_mul_f32 v[148:149], v[170:171], v[148:149]
	v_cvt_pk_bf16_f32 v150, v144, v145
	v_cvt_pk_bf16_f32 v151, v148, v149
	ds_write2_b32 v139, v152, v153 offset0:16 offset1:84
	ds_write2_b32 v142, v136, v137 offset0:16 offset1:84
	ds_write2_b32 v140, v150, v151 offset0:16 offset1:84
	v_lshlrev_b32_e32 v136, 16, v63
	v_and_b32_e32 v137, 0xffff0000, v63
	v_lshlrev_b32_e32 v144, 16, v67
	v_and_b32_e32 v145, 0xffff0000, v67
	v_lshlrev_b32_e32 v148, 16, v71
	v_and_b32_e32 v149, 0xffff0000, v71
	v_lshlrev_b32_e32 v150, 16, v75
	v_and_b32_e32 v151, 0xffff0000, v75
	v_pk_mul_f32 v[152:153], v[94:95], v[144:145]
	v_pk_mul_f32 v[144:145], v[86:87], v[144:145]
	v_pk_fma_f32 v[152:153], v[86:87], v[136:137], v[152:153] neg_lo:[0,0,1] neg_hi:[0,0,1]
	v_pk_fma_f32 v[136:137], v[94:95], v[136:137], v[144:145]
	v_pk_mul_f32 v[144:145], v[110:111], v[150:151]
	v_pk_mul_f32 v[150:151], v[102:103], v[150:151]
	v_pk_fma_f32 v[144:145], v[102:103], v[148:149], v[144:145] neg_lo:[0,0,1] neg_hi:[0,0,1]
	v_pk_fma_f32 v[148:149], v[110:111], v[148:149], v[150:151]
	v_cvt_pk_bf16_f32 v152, v152, v144
	v_cvt_pk_bf16_f32 v153, v153, v145
	v_cvt_pk_bf16_f32 v136, v136, v148
	v_cvt_pk_bf16_f32 v137, v137, v149
	v_lshlrev_b32_e32 v144, 16, v79
	v_lshlrev_b32_e32 v145, 16, v83
	v_pk_mul_f32 v[144:145], v[170:171], v[144:145]
	v_and_b32_e32 v148, 0xffff0000, v79
	v_and_b32_e32 v149, 0xffff0000, v83
	v_pk_mul_f32 v[148:149], v[170:171], v[148:149]
	v_cvt_pk_bf16_f32 v150, v144, v145
	v_cvt_pk_bf16_f32 v151, v148, v149
	ds_write2_b32 v139, v152, v153 offset0:152 offset1:220
	ds_write2_b32 v142, v136, v137 offset0:152 offset1:220
	ds_write2_b32 v140, v150, v151 offset0:152 offset1:220
	s_cmp_gt_u32 s38, 26
	ds_read_b128 v[148:151], v203
	ds_read_b128 v[224:227], v204
	s_cbranch_scc1 .LBB0_200
; __device__ __forceinline__ void ret_scan(const bf16_t* proj, const float* cosT, const float* sinT, const float* decay, bf16_t* states, unsigned char* lds, int tid, int bx) {
;     ...
;             SCAN_WRITE(A, 0); if (step + 4 <= 30) SCAN_LOAD(A, SCAN_NCH(step + 4));
	s_and_b64 s[0:1], s[36:37], exec
	s_cselect_b32 s0, s34, s35
	v_lshl_add_u32 v84, s0, 7, v183
	v_add_u32_e32 v62, s29, v84
	v_mov_b64_e32 v[60:61], s[14:15]
	v_mad_i64_i32 v[76:77], s[0:1], v62, s59, v[60:61]
	v_lshl_add_u64 v[68:69], v[76:77], 0, v[154:155]
	s_lshl_b32 s6, s30, 1
	v_add_co_u32_e32 v72, vcc, 0x2000, v68
	v_lshl_add_u64 v[76:77], v[76:77], 0, s[6:7]
	v_lshlrev_b32_e32 v84, 6, v84
	v_addc_co_u32_e32 v73, vcc, 0, v69, vcc
	v_lshl_add_u64 v[76:77], v[76:77], 0, v[154:155]
	v_ashrrev_i32_e32 v85, 31, v84
	v_add_co_u32_e32 v80, vcc, 0x2000, v76
	v_lshlrev_b64 v[84:85], 2, v[84:85]
	s_nop 0
	v_addc_co_u32_e32 v81, vcc, 0, v77, vcc
	v_lshl_add_u64 v[104:105], v[160:161], 0, v[84:85]
	v_lshl_add_u64 v[112:113], v[162:163], 0, v[84:85]
	global_load_dwordx4 v[60:63], v[68:69], off offset:1536
	global_load_dwordx4 v[64:67], v[68:69], off offset:1664
	s_nop 0
	global_load_dwordx4 v[68:71], v[72:73], off
	s_nop 0
	global_load_dwordx4 v[72:75], v[72:73], off offset:128
	s_nop 0
	global_load_dwordx4 v[76:79], v[76:77], off offset:3072
	s_nop 0
	global_load_dwordx4 v[80:83], v[80:81], off offset:1536
	s_nop 0
	global_load_dwordx4 v[84:87], v[104:105], off offset:16
	global_load_dwordx4 v[88:91], v[104:105], off
	global_load_dwordx4 v[92:95], v[112:113], off offset:16
	global_load_dwordx4 v[96:99], v[112:113], off
	global_load_dwordx4 v[100:103], v[104:105], off offset:272
	s_nop 0
	global_load_dwordx4 v[104:107], v[104:105], off offset:256
	s_nop 0
	global_load_dwordx4 v[108:111], v[112:113], off offset:272
	s_nop 0
	global_load_dwordx4 v[112:115], v[112:113], off offset:256
	s_branch .LBB0_200
